# G epilogue P prefetch + D2 chunk-loop store-aware vmcnt + L epilogue roww loads hoisted
# baseline (speedup 1.0000x reference)
; __device__ __forceinline__ void phase_scan_chunk(const Args& a, LAS unsigned char* lds, const WCtx& w, int l) {
;     ...
;             GLA_LOAD(0);
.LBB0_1199:
	s_bfe_u32 s9, s7, 0x40002
	s_lshl_b32 s2, s7, 6
	s_and_b32 s13, s2, 0xc0
	s_lshl_b32 s8, s9, 8
	v_readlane_b32 s2, v253, 41
	s_bitset1_b32 s8, 15
	v_readlane_b32 s3, v253, 42
	v_or_b32_e32 v4, s8, v97
	v_readlane_b32 s16, v254, 32
	v_mov_b64_e32 v[2:3], s[2:3]
	v_mad_u64_u32 v[2:3], s[2:3], v4, s15, v[2:3]
	v_readlane_b32 s17, v254, 33
	s_lshl_b32 s16, s13, 1
	s_waitcnt vmcnt(0)
	v_lshlrev_b32_e32 v50, 1, v116
	v_lshl_add_u64 v[2:3], v[2:3], 0, s[16:17]
	v_lshl_add_u64 v[2:3], v[2:3], 0, v[50:51]
	v_lshl_add_u64 v[6:7], v[2:3], 0, v[44:45]
	v_lshl_add_u64 v[8:9], v[6:7], 0, v[44:45]
	v_lshl_add_u64 v[10:11], v[8:9], 0, v[44:45]
	v_lshl_add_u64 v[12:13], v[10:11], 0, v[44:45]
	v_lshl_add_u64 v[14:15], v[12:13], 0, v[44:45]
	v_lshl_add_u64 v[16:17], v[14:15], 0, v[44:45]
	v_lshl_add_u64 v[18:19], v[16:17], 0, v[44:45]
	v_lshl_add_u64 v[20:21], v[18:19], 0, v[44:45]
	v_lshl_add_u64 v[22:23], v[20:21], 0, v[44:45]
	s_waitcnt vmcnt(0)
	v_lshl_add_u64 v[24:25], v[22:23], 0, v[44:45]
	v_lshl_add_u64 v[26:27], v[24:25], 0, v[44:45]
	v_lshl_add_u64 v[28:29], v[26:27], 0, v[44:45]
	s_movk_i32 s2, 0xc00
	v_lshl_add_u64 v[30:31], v[28:29], 0, v[44:45]
	v_mad_u64_u32 v[4:5], s[2:3], v4, s2, v[42:43]
	v_lshl_add_u64 v[32:33], v[30:31], 0, v[44:45]
	s_lshl_b32 s2, s13, 2
	s_mov_b32 s3, s17
	v_lshl_add_u64 v[34:35], v[32:33], 0, v[44:45]
	v_lshl_add_u64 v[4:5], v[4:5], 0, s[2:3]
	global_load_ushort v162, v[2:3], off
	global_load_ushort v163, v[6:7], off
	global_load_ushort v164, v[8:9], off
	global_load_ushort v165, v[10:11], off
	global_load_ushort v166, v[12:13], off
	global_load_ushort v167, v[14:15], off
	global_load_ushort v168, v[16:17], off
	global_load_ushort v169, v[18:19], off
	global_load_ushort v170, v[20:21], off
	global_load_ushort v171, v[22:23], off
	global_load_ushort v172, v[24:25], off
	global_load_ushort v173, v[26:27], off
	global_load_ushort v174, v[28:29], off
	global_load_ushort v175, v[30:31], off
	global_load_ushort v176, v[32:33], off
	global_load_ushort v177, v[34:35], off
	v_lshlrev_b32_e32 v50, 2, v116
	global_load_ushort v178, v[2:3], off offset:512
	global_load_ushort v179, v[6:7], off offset:512
	global_load_ushort v180, v[8:9], off offset:512
	global_load_ushort v181, v[10:11], off offset:512
	global_load_ushort v182, v[12:13], off offset:512
	global_load_ushort v183, v[14:15], off offset:512
	global_load_ushort v184, v[16:17], off offset:512
	global_load_ushort v185, v[18:19], off offset:512
	global_load_ushort v186, v[20:21], off offset:512
	global_load_ushort v187, v[22:23], off offset:512
	global_load_ushort v188, v[24:25], off offset:512
	global_load_ushort v189, v[26:27], off offset:512
	global_load_ushort v190, v[28:29], off offset:512
	global_load_ushort v191, v[30:31], off offset:512
	global_load_ushort v192, v[32:33], off offset:512
	global_load_ushort v193, v[34:35], off offset:512
	v_lshl_add_u64 v[2:3], v[4:5], 0, v[50:51]
	v_lshl_add_u64 v[4:5], v[2:3], 0, v[46:47]
	v_lshl_add_u64 v[6:7], v[4:5], 0, v[46:47]
	v_lshl_add_u64 v[8:9], v[6:7], 0, v[46:47]
	v_lshl_add_u64 v[10:11], v[8:9], 0, v[46:47]
	global_load_dword v50, v[2:3], off
	global_load_dword v194, v[4:5], off
	global_load_dword v195, v[6:7], off
	global_load_dword v197, v[8:9], off
	global_load_dword v199, v[10:11], off
	v_lshl_add_u64 v[2:3], v[10:11], 0, v[46:47]
	global_load_dword v200, v[2:3], off
	v_lshl_add_u64 v[2:3], v[2:3], 0, v[46:47]
	global_load_dword v201, v[2:3], off
	v_lshl_add_u64 v[2:3], v[2:3], 0, v[46:47]
	global_load_dword v202, v[2:3], off
	v_lshl_add_u64 v[2:3], v[2:3], 0, v[46:47]
	global_load_dword v203, v[2:3], off
	v_lshl_add_u64 v[2:3], v[2:3], 0, v[46:47]
	global_load_dword v204, v[2:3], off
	v_lshl_add_u64 v[2:3], v[2:3], 0, v[46:47]
	global_load_dword v205, v[2:3], off
	v_lshl_add_u64 v[2:3], v[2:3], 0, v[46:47]
	global_load_dword v206, v[2:3], off
	v_lshl_add_u64 v[2:3], v[2:3], 0, v[46:47]
	global_load_dword v207, v[2:3], off
	v_lshl_add_u64 v[2:3], v[2:3], 0, v[46:47]
	global_load_dword v208, v[2:3], off
	v_lshl_add_u64 v[2:3], v[2:3], 0, v[46:47]
	global_load_dword v209, v[2:3], off
	v_lshl_add_u64 v[2:3], v[2:3], 0, v[46:47]
	global_load_dword v210, v[2:3], off
	s_mov_b32 s13, s17
	v_writelane_b32 v254, s12, 32
	v_mov_b32_e32 v66, 0
	v_lshl_add_u64 v[60:61], v[40:41], 0, s[16:17]
	v_writelane_b32 v254, s13, 33
	v_lshl_add_u64 v[62:63], v[48:49], 0, s[16:17]
	v_lshl_add_u64 v[64:65], v[52:53], 0, s[2:3]
	s_lshl_b32 s9, s9, 11
	s_mov_b32 s13, 0
	s_mov_b32 s23, 0
	s_mov_b32 s25, 0
	v_mov_b32_e32 v67, v66
	v_mov_b32_e32 v68, v66
	v_mov_b32_e32 v69, v66
	v_mov_b32_e32 v70, v66
	v_mov_b32_e32 v71, v66
	v_mov_b32_e32 v72, v66
	v_mov_b32_e32 v73, v66
	v_mov_b32_e32 v74, v66
	v_mov_b32_e32 v75, v66
	v_mov_b32_e32 v76, v66
	v_mov_b32_e32 v77, v66
	v_mov_b32_e32 v78, v66
	v_mov_b32_e32 v79, v66
	v_mov_b32_e32 v80, v66
	v_mov_b32_e32 v81, v66
	s_waitcnt vmcnt(0)
	s_branch .LBB0_1201

; __device__ __forceinline__ float bf2f(unsigned b) { return __uint_as_float(b << 16); }
; #define LBAR() asm volatile("s_waitcnt lgkmcnt(0)\n\ts_barrier" ::: "memory")
; __device__ __forceinline__ void phase_scan_chunk(const Args& a, LAS unsigned char* lds, const WCtx& w, int l) {
;     ...
; #pragma unroll
;                 for (int ii = 0; ii < 16; ++ii) { kk[ii] = 1.0f - __expf(rz[ii]); run += rz[ii]; lc[ii] = run; qq[ii] = bf2f(rq[ii]); vvv[ii] = bf2f(rv[ii]); }
;                 QSUM[iq * 64 + d] = run;
;                 LBAR();
.LBB0_1201:
	s_waitcnt vmcnt(31)
	v_add_f32_e32 v24, 0, v50
	s_waitcnt vmcnt(30)
	v_add_f32_e32 v8, v24, v194
	s_waitcnt vmcnt(29)
	v_add_f32_e32 v10, v8, v195
	s_waitcnt vmcnt(28)
	v_add_f32_e32 v12, v10, v197
	s_waitcnt vmcnt(27)
	v_add_f32_e32 v14, v12, v199
	s_waitcnt vmcnt(26)
	v_add_f32_e32 v16, v14, v200
	s_waitcnt vmcnt(25)
	v_add_f32_e32 v18, v16, v201
	s_waitcnt vmcnt(24)
	v_add_f32_e32 v20, v18, v202
	s_waitcnt vmcnt(23)
	v_add_f32_e32 v21, v20, v203
	s_waitcnt vmcnt(22)
	v_add_f32_e32 v19, v21, v204
	s_waitcnt vmcnt(21)
	v_add_f32_e32 v17, v19, v205
	s_waitcnt vmcnt(20)
	v_add_f32_e32 v15, v17, v206
	s_waitcnt vmcnt(19)
	v_add_f32_e32 v13, v15, v207
	s_waitcnt vmcnt(18)
	v_add_f32_e32 v11, v13, v208
	v_mul_f32_e32 v2, 0x3fb8aa3b, v50
	s_waitcnt vmcnt(17)
	v_add_f32_e32 v9, v11, v209
	v_exp_f32_e32 v2, v2
	s_waitcnt vmcnt(16)
	v_add_f32_e32 v6, v9, v210
	ds_write_b32 v98, v6
	s_waitcnt lgkmcnt(0)
	s_barrier
	ds_read2st64_b32 v[4:5], v99 offset1:1
	v_sub_f32_e32 v23, 1.0, v2
	ds_read2st64_b32 v[2:3], v99 offset0:2 offset1:3
	v_lshlrev_b32_e32 v22, 16, v162
	s_waitcnt lgkmcnt(1)
	v_cndmask_b32_e64 v7, v4, 0, s[36:37]
	v_cndmask_b32_e64 v25, 0, v5, s[40:41]
	v_add_f32_e32 v7, v7, v25
	s_waitcnt lgkmcnt(0)
	v_cndmask_b32_e64 v25, 0, v2, s[44:45]
	v_add_f32_e32 v7, v7, v25
	v_add_f32_e32 v5, v4, v5
	v_add_f32_e32 v4, v24, v7
	v_mul_f32_e32 v24, 0x3fb8aa3b, v4
	v_sub_f32_e32 v4, v5, v4
	v_exp_f32_e32 v25, v24
	v_min_f32_e32 v4, 0x42a00000, v4
	v_mul_f32_e32 v4, 0x3fb8aa3b, v4
	v_exp_f32_e32 v24, v4
	v_mul_f32_e32 v4, v25, v22
	v_cvt_pk_bf16_f32 v4, v4, v4
	ds_write_b16 v111, v4
	v_mul_f32_e32 v4, v23, v24
	v_cvt_pk_bf16_f32 v26, v4, v4
	ds_write_b16 v111, v26 offset:9216
	s_and_saveexec_b64 s[2:3], s[42:43]
	s_xor_b64 s[2:3], exec, s[2:3]
	s_cbranch_execz .LBB0_1203
	v_max_f32_e32 v22, v25, v25
	v_max_f32_e32 v22, 0x554ad2e, v22
	v_rcp_f32_e32 v22, v22
	s_nop 0
	v_mul_f32_e32 v22, v23, v22
	v_cvt_pk_bf16_f32 v22, v22, v22
	ds_write_b16 v112, v22 offset:23040

; __device__ __forceinline__ float softplus_acc(float x) { return x > 20.f ? x : log1pf(expf(x)); }
; __device__ __forceinline__ void phase_scan_chunk(const Args& a, LAS unsigned char* lds, const WCtx& w, int l) {
;     ...
;             SD_LOAD(0, 0); SD_LOAD(1, 1);
;     ...
;                 if (gw4 == 0) { const float sp = softplus_acc(rs0s[u] + dtb); float g = -al * sp;
.LBB0_1302:
	s_nop 0
	v_readlane_b32 s2, v254, 5
	v_readlane_b32 s3, v254, 6
	v_lshl_add_u32 v4, s29, 1, v121
	v_readlane_b32 s30, v255, 13
	v_mov_b64_e32 v[2:3], s[2:3]
	s_mov_b32 s2, 0x1200000
	v_mad_i64_i32 v[2:3], s[2:3], v4, s2, v[2:3]
	s_waitcnt vmcnt(13)
	v_mul_f32_e32 v4, 0x3fb8aa3b, v12
	v_rndne_f32_e32 v5, v4
	v_sub_f32_e32 v6, v4, v5
	v_fma_f32 v4, v12, s12, -v4
	v_fmac_f32_e32 v4, 0x32a5705f, v12
	v_readlane_b32 s2, v254, 32
	v_add_f32_e32 v4, v6, v4
	v_readlane_b32 s3, v254, 33
	s_lshl_b32 s2, s22, 1
	v_exp_f32_e32 v4, v4
	v_cvt_i32_f32_e32 v5, v5
	v_lshl_add_u64 v[2:3], v[2:3], 0, s[2:3]
	v_writelane_b32 v254, s2, 32
	v_mov_b32_e32 v135, v51
	v_cmp_ngt_f32_e32 vcc, s13, v12
	v_writelane_b32 v254, s3, 33
	s_mov_b32 s2, s30
	v_lshl_add_u64 v[2:3], v[2:3], 0, s[2:3]
	v_lshl_add_u64 v[136:137], v[2:3], 0, v[134:135]
	v_ldexp_f32 v2, v4, v5
	s_bfe_u32 s2, s25, 0x60001
	v_cndmask_b32_e32 v2, 0, v2, vcc
	v_cmp_nlt_f32_e32 vcc, s15, v12
	s_mulk_i32 s2, 0x48
	s_cmp_eq_u32 s29, 2
	v_cndmask_b32_e32 v135, v235, v2, vcc
	v_add_u32_e32 v2, s2, v189
	s_mov_b32 s22, s30
	v_ashrrev_i32_e32 v3, 31, v2
	s_cselect_b64 s[84:85], -1, 0
	s_cmp_lg_u32 s29, 2
	v_readlane_b32 s31, v255, 14
	v_writelane_b32 v255, s22, 13
	v_lshlrev_b64 v[2:3], 13, v[2:3]
	s_cselect_b64 s[86:87], -1, 0
	s_lshl_b32 s2, s90, 5
	s_mov_b64 s[94:95], 0x800
	v_writelane_b32 v255, s23, 14
	v_lshl_add_u64 v[138:139], v[132:133], 0, v[2:3]
	s_lshl_b32 s11, s23, 11
	s_mov_b32 s29, 64
	s_and_b32 s30, s2, 64
	v_or_b32_e32 v213, s28, v179
	v_or_b32_e32 v214, s28, v186
	v_or_b32_e32 v215, s28, v187
	v_or_b32_e32 v216, s28, v188
	s_mov_b32 s31, 0
	s_movk_i32 s34, 0xffc0
	v_mov_b32_e32 v141, v140
	v_mov_b32_e32 v154, v140
	v_mov_b32_e32 v155, v140
	v_mov_b32_e32 v152, v140
	v_mov_b32_e32 v153, v140
	v_mov_b32_e32 v150, v140
	v_mov_b32_e32 v151, v140
	v_mov_b32_e32 v148, v140
	v_mov_b32_e32 v149, v140
	v_mov_b32_e32 v146, v140
	v_mov_b32_e32 v147, v140
	v_mov_b32_e32 v144, v140
	v_mov_b32_e32 v145, v140
	v_mov_b32_e32 v142, v140
	v_mov_b32_e32 v143, v140
	s_waitcnt vmcnt(0)
	s_branch .LBB0_1304

; __device__ __forceinline__ float sigmoid_acc(float x) { return 1.0f / (1.0f + expf(-x)); }
; __device__ __forceinline__ float softplus_acc(float x) { return x > 20.f ? x : log1pf(expf(x)); }
; __device__ __forceinline__ void phase_scan_chunk(const Args& a, LAS unsigned char* lds, const WCtx& w, int l) {
;     ...
;                 if (gw4 == 0) { const float sp = softplus_acc(rs0s[u] + dtb); float g = -al * sp;
;                     g = wave_scan(g);
;                     G[lane] = g; EG[lane] = __expf(g); BD[lane] = (mix == 1) ? sigmoid_acc(rs1s[u]) : sp; }
.LBB0_1304:
	s_and_b64 vcc, exec, s[70:71]
	s_cbranch_vccnz .LBB0_1310
	s_waitcnt vmcnt(22)
	v_add_f32_e32 v2, v208, v209
	v_cmp_nlt_f32_e32 vcc, s10, v2
	s_and_saveexec_b64 s[2:3], vcc
	s_cbranch_execz .LBB0_1307
	v_mul_f32_e32 v3, 0x3fb8aa3b, v2
	v_rndne_f32_e32 v4, v3
	v_sub_f32_e32 v5, v3, v4
	v_fma_f32 v3, v2, s12, -v3
	v_fmac_f32_e32 v3, 0x32a5705f, v2
	v_add_f32_e32 v3, v5, v3
	v_cvt_i32_f32_e32 v4, v4
	v_exp_f32_e32 v3, v3
	v_cmp_ngt_f32_e32 vcc, s13, v2
	v_ldexp_f32 v3, v3, v4
	s_nop 0
	v_cndmask_b32_e32 v3, 0, v3, vcc
	v_cmp_nlt_f32_e32 vcc, s15, v2
	s_nop 1
	v_cndmask_b32_e32 v16, v235, v3, vcc
	v_add_f32_e32 v4, 1.0, v16
	v_add_f32_e32 v2, -1.0, v4
	v_sub_f32_e32 v3, v2, v4
	v_add_f32_e32 v3, 1.0, v3
	v_sub_f32_e32 v2, v16, v2
	v_add_f32_e32 v5, v2, v3
	v_frexp_mant_f32_e32 v6, v4
	v_cvt_f64_f32_e32 v[2:3], v4
	v_frexp_exp_i32_f64_e32 v2, v[2:3]
	v_cmp_gt_f32_e32 vcc, s16, v6
	s_nop 1
	v_subbrev_co_u32_e32 v10, vcc, 0, v2, vcc
	v_sub_u32_e32 v2, 0, v10
	v_ldexp_f32 v3, v4, v2
	v_add_f32_e32 v4, -1.0, v3
	v_add_f32_e32 v6, 1.0, v3
	v_ldexp_f32 v2, v5, v2
	v_add_f32_e32 v5, 1.0, v4
	v_add_f32_e32 v7, -1.0, v6
	v_sub_f32_e32 v5, v3, v5
	v_sub_f32_e32 v3, v3, v7
	v_add_f32_e32 v5, v2, v5
	v_add_f32_e32 v2, v2, v3
	v_add_f32_e32 v11, v6, v2
	v_rcp_f32_e32 v13, v11
	v_sub_f32_e32 v3, v6, v11
	v_add_f32_e32 v12, v2, v3
	v_add_f32_e32 v3, v4, v5
	v_mul_f32_e32 v15, v3, v13
	v_sub_f32_e32 v2, v4, v3
	v_mul_f32_e32 v4, v11, v15
	v_fma_f32 v6, v15, v11, -v4
	v_fmac_f32_e32 v6, v15, v12
	v_add_f32_e32 v14, v5, v2
	v_add_f32_e32 v2, v4, v6
	v_sub_f32_e32 v5, v3, v2
	v_pk_add_f32 v[8:9], v[2:3], v[4:5] neg_lo:[0,1] neg_hi:[0,1]
	v_mov_b32_e32 v7, v2
	v_pk_add_f32 v[2:3], v[8:9], v[6:7] neg_lo:[0,1] neg_hi:[0,1]
	v_cmp_neq_f32_e32 vcc, s24, v16
	v_add_f32_e32 v3, v14, v3
	v_add_f32_e32 v2, v2, v3
	v_add_f32_e32 v3, v5, v2
	v_mul_f32_e32 v14, v13, v3
	v_mul_f32_e32 v4, v11, v14
	v_fma_f32 v6, v14, v11, -v4
	v_fmac_f32_e32 v6, v14, v12
	v_sub_f32_e32 v5, v5, v3
	v_add_f32_e32 v11, v2, v5
	v_add_f32_e32 v2, v4, v6
	v_sub_f32_e32 v5, v3, v2
	v_pk_add_f32 v[8:9], v[2:3], v[4:5] neg_lo:[0,1] neg_hi:[0,1]
	v_mov_b32_e32 v7, v2
	v_pk_add_f32 v[2:3], v[8:9], v[6:7] neg_lo:[0,1] neg_hi:[0,1]
	s_nop 0
	v_add_f32_e32 v3, v11, v3
	v_add_f32_e32 v2, v2, v3
	v_add_f32_e32 v3, v15, v14
	v_add_f32_e32 v2, v5, v2
	v_sub_f32_e32 v4, v3, v15
	v_mul_f32_e32 v2, v13, v2
	v_sub_f32_e32 v4, v14, v4
	v_add_f32_e32 v4, v4, v2
	v_add_f32_e32 v6, v3, v4
	v_mul_f32_e32 v7, v6, v6
	v_fmamk_f32 v2, v7, 0x3e9b6dac, v250
	v_fmaak_f32 v199, v7, v2, 0x3f2aaada
	v_cvt_f32_i32_e32 v2, v10
	v_sub_f32_e32 v3, v6, v3
	v_sub_f32_e32 v3, v4, v3
	v_ldexp_f32 v8, v3, 1
	v_mul_f32_e32 v3, v6, v7
	v_ldexp_f32 v5, v6, 1
	v_pk_mul_f32 v[6:7], v[2:3], v[198:199]
	s_nop 0
	v_fma_f32 v4, v2, s17, -v6
	v_fmac_f32_e32 v4, 0xb102e308, v2
	v_pk_add_f32 v[2:3], v[6:7], v[4:5]
	s_nop 0
	v_sub_f32_e32 v5, v3, v5
	v_sub_f32_e32 v5, v7, v5
	v_add_f32_e32 v9, v8, v5
	v_mov_b32_e32 v8, v6
	v_pk_add_f32 v[6:7], v[2:3], v[6:7] neg_lo:[0,1] neg_hi:[0,1]
	v_pk_add_f32 v[10:11], v[2:3], v[8:9]
	v_mov_b32_e32 v5, v2
	v_mov_b32_e32 v7, v11
	v_pk_add_f32 v[12:13], v[4:5], v[6:7] neg_lo:[0,1] neg_hi:[0,1]
	v_pk_add_f32 v[4:5], v[4:5], v[6:7]
	v_mov_b32_e32 v8, v9
	v_pk_add_f32 v[6:7], v[4:5], v[2:3] op_sel:[1,0] op_sel_hi:[0,1] neg_lo:[0,1] neg_hi:[0,1]
	v_pk_add_f32 v[14:15], v[10:11], v[6:7] op_sel_hi:[1,0] neg_lo:[0,1] neg_hi:[0,1]
	v_mov_b32_e32 v10, v11
	v_mov_b32_e32 v11, v5
	v_pk_mov_b32 v[6:7], v[2:3], v[6:7] op_sel:[1,0]
	v_mov_b32_e32 v9, v2
	v_pk_add_f32 v[6:7], v[10:11], v[6:7] neg_lo:[0,1] neg_hi:[0,1]
	v_mov_b32_e32 v14, v12
	v_pk_add_f32 v[2:3], v[8:9], v[6:7] neg_lo:[0,1] neg_hi:[0,1]
	v_mov_b32_e32 v13, v5
	v_pk_add_f32 v[6:7], v[14:15], v[2:3]
	s_nop 0
	v_pk_add_f32 v[8:9], v[6:7], v[6:7] op_sel:[0,1] op_sel_hi:[1,0]
	s_nop 0
	v_pk_add_f32 v[4:5], v[4:5], v[8:9] op_sel:[1,0] op_sel_hi:[0,1]
	v_mov_b32_e32 v7, v4
	v_pk_add_f32 v[10:11], v[6:7], v[12:13] neg_lo:[0,1] neg_hi:[0,1]
	v_mov_b32_e32 v3, v8
	v_sub_f32_e32 v5, v6, v10
	v_pk_add_f32 v[2:3], v[2:3], v[10:11] neg_lo:[0,1] neg_hi:[0,1]
	v_sub_f32_e32 v5, v12, v5
	v_add_f32_e32 v2, v2, v5
	v_add_f32_e32 v2, v2, v3
	v_add_f32_e32 v2, v4, v2
	v_cndmask_b32_e32 v2, v235, v2, vcc
	v_cmp_lt_f32_e64 vcc, |v16|, s18
	s_nop 1
	v_cndmask_b32_e32 v2, v2, v16, vcc

; #define LAS __attribute__((address_space(3)))
; __device__ __forceinline__ bf16 bfr(float x) { return (bf16)cvt_pk_bf16(x, x); }
; __device__ __forceinline__ void unpack8(const v4u u, float (&f)[8]) { f[0] = bf2f(u.x & 0xffffu); f[1] = bf2f(u.x >> 16); f[2] = bf2f(u.y & 0xffffu); f[3] = bf2f(u.y >> 16); f[4] = bf2f(u.z & 0xffffu); f[5] = bf2f(u.z >> 16); f[6] = bf2f(u.w & 0xffffu); f[7] = bf2f(u.w >> 16); }
; __device__ __forceinline__ void phase_scan_chunk(const Args& a, LAS unsigned char* lds, const WCtx& w, int l) {
;     ...
;                 { const float gi = G[i], g63 = G[63]; const float kdsc = __expf(g63 - gi), vsc = (mix == 2) ? BD[i] : 1.0f;
;                   const int colsw = ((((i >> 3) ^ dq) << 3) | (i & 7)); LAS bf16* kdb = TKD + 16 * dq * TS + colsw; LAS bf16* vtb = TVT + 16 * dq * TS + colsw;
;                   *(LAS v4u*)(TQ + i * TS + 16 * dq) = rq0s[u]; *(LAS v4u*)(TQ + i * TS + 16 * dq + 8) = rq1s[u];
;                   *(LAS v4u*)(TK + i * TS + 16 * dq) = rk0s[u]; *(LAS v4u*)(TK + i * TS + 16 * dq + 8) = rk1s[u];
;                   float kf[8];
;                   unpack8(rk0s[u], kf);
; #pragma unroll
;                   for (int t = 0; t < 8; ++t) kdb[t * TS] = bfr(kf[t] * kdsc);
;                   unpack8(rk1s[u], kf);
; #pragma unroll
;                   for (int t = 0; t < 8; ++t) kdb[(8 + t) * TS] = bfr(kf[t] * kdsc);
;                   if (mix == 2) { unpack8(ra0s[u], kf);
; #pragma unroll
;                       for (int t = 0; t < 8; ++t) vtb[t * TS] = bfr(kf[t] * vsc);
;                       unpack8(ra1s[u], kf);
; #pragma unroll
;                       for (int t = 0; t < 8; ++t) vtb[(8 + t) * TS] = bfr(kf[t] * vsc); }
;                   else { *(LAS v4u*)(TX + i * TS + 16 * dq) = ra0s[u]; *(LAS v4u*)(TX + i * TS + 16 * dq + 8) = ra1s[u];
;                          *(LAS v4u*)(TVT + swz(i, 16 * dq)) = rb0s[u]; *(LAS v4u*)(TVT + swz(i, 16 * dq + 8)) = rb1s[u]; } }
.LBB0_1312:
	s_waitcnt lgkmcnt(0)
	v_sub_f32_e32 v3, v4, v3
	v_mul_f32_e32 v3, 0x3fb8aa3b, v3
	v_exp_f32_e32 v3, v3
	s_waitcnt vmcnt(24)
	v_lshlrev_b32_e32 v4, 16, v72
	s_waitcnt vmcnt(22)
	ds_write_b128 v170, v[80:83]
	ds_write_b128 v170, v[76:79] offset:16
	ds_write_b128 v170, v[72:75] offset:9216
	ds_write_b128 v170, v[68:71] offset:9232
	v_and_b32_e32 v5, 0xffff0000, v72
	v_mul_f32_e32 v4, v3, v4
	v_cvt_pk_bf16_f32 v4, v4, v4
	ds_write_b16 v169, v4 offset:27648
	v_mul_f32_e32 v4, v3, v5
	v_lshlrev_b32_e32 v6, 16, v73
	v_cvt_pk_bf16_f32 v4, v4, v4
	ds_write_b16 v169, v4 offset:27792
	v_mul_f32_e32 v4, v3, v6
	v_and_b32_e32 v7, 0xffff0000, v73
	v_cvt_pk_bf16_f32 v4, v4, v4
	ds_write_b16 v169, v4 offset:27936
	v_mul_f32_e32 v4, v3, v7
	v_lshlrev_b32_e32 v8, 16, v74
	v_cvt_pk_bf16_f32 v4, v4, v4
	ds_write_b16 v169, v4 offset:28080
	v_mul_f32_e32 v4, v3, v8
	v_and_b32_e32 v9, 0xffff0000, v74
	v_cvt_pk_bf16_f32 v4, v4, v4
	ds_write_b16 v169, v4 offset:28224
	v_mul_f32_e32 v4, v3, v9
	v_lshlrev_b32_e32 v10, 16, v75
	v_cvt_pk_bf16_f32 v4, v4, v4
	ds_write_b16 v169, v4 offset:28368
	v_mul_f32_e32 v4, v3, v10
	v_and_b32_e32 v11, 0xffff0000, v75
	v_cvt_pk_bf16_f32 v4, v4, v4
	ds_write_b16 v169, v4 offset:28512
	v_mul_f32_e32 v4, v3, v11
	v_cvt_pk_bf16_f32 v4, v4, v4
	ds_write_b16 v169, v4 offset:28656
	v_lshlrev_b32_e32 v4, 16, v68
	v_mul_f32_e32 v4, v3, v4
	v_and_b32_e32 v5, 0xffff0000, v68
	v_cvt_pk_bf16_f32 v4, v4, v4
	ds_write_b16 v169, v4 offset:28800
	v_mul_f32_e32 v4, v3, v5
	v_lshlrev_b32_e32 v6, 16, v69
	v_cvt_pk_bf16_f32 v4, v4, v4
	ds_write_b16 v169, v4 offset:28944
	v_mul_f32_e32 v4, v3, v6
	v_and_b32_e32 v7, 0xffff0000, v69
	v_cvt_pk_bf16_f32 v4, v4, v4
	ds_write_b16 v169, v4 offset:29088
	v_mul_f32_e32 v4, v3, v7
	v_lshlrev_b32_e32 v8, 16, v70
	v_cvt_pk_bf16_f32 v4, v4, v4
	ds_write_b16 v169, v4 offset:29232
	v_mul_f32_e32 v4, v3, v8
	v_and_b32_e32 v9, 0xffff0000, v70
	v_cvt_pk_bf16_f32 v4, v4, v4
	ds_write_b16 v169, v4 offset:29376
	v_mul_f32_e32 v4, v3, v9
	v_lshlrev_b32_e32 v10, 16, v71
	v_and_b32_e32 v11, 0xffff0000, v71
	v_cvt_pk_bf16_f32 v4, v4, v4
	ds_write_b16 v169, v4 offset:29520
	v_mul_f32_e32 v4, v3, v10
	v_mul_f32_e32 v3, v3, v11
	s_mov_b64 s[2:3], -1
	s_and_b64 vcc, exec, s[86:87]
	v_cvt_pk_bf16_f32 v4, v4, v4
	ds_write_b16 v169, v4 offset:29664
	v_cvt_pk_bf16_f32 v3, v3, v3
	ds_write_b16 v169, v3 offset:29808
	s_cbranch_vccz .LBB0_1314
	ds_write_b128 v170, v[64:67] offset:18432
	ds_write_b128 v170, v[60:63] offset:18448
	ds_write_b128 v171, v[52:55] offset:36864
	ds_write_b128 v172, v[56:59] offset:36864
	s_mov_b64 s[2:3], 0

; __device__ __forceinline__ unsigned pk4_fp8(float a, float b, float c, float d) { int w = 0; w = __builtin_amdgcn_cvt_pk_fp8_f32(a, b, w, false); w = __builtin_amdgcn_cvt_pk_fp8_f32(c, d, w, true); return (unsigned)w; }
;     __device__ __forceinline__ void operator()(EPI_SIG) const {
;         const int row0 = u.pm * 256 + wr * 64 + fr, col0 = u.pn * 256 + wc * 32 + 8 * fq;
; #pragma unroll
;         for (int ai = 0; ai < 2; ++ai)
; #pragma unroll
;             for (int m = 0; m < 4; ++m) { const int row = row0 + ai * 128 + m * 16; const float s = roww[row] * 64.0f; unsigned char* rowp = O + (size_t)row * 1024 + col0;
; #pragma unroll
;                 for (int bj = 0; bj < 2; ++bj) { const f32x4 v0 = acc[ai][bj][m][0] * s, v1 = acc[ai][bj][m][1] * s; v2u w;
;                     w.x = pk4_fp8(fminf(fmaxf(v0[0], -448.f), 448.f), fminf(fmaxf(v0[1], -448.f), 448.f), fminf(fmaxf(v0[2], -448.f), 448.f), fminf(fmaxf(v0[3], -448.f), 448.f));
;                     w.y = pk4_fp8(fminf(fmaxf(v1[0], -448.f), 448.f), fminf(fmaxf(v1[1], -448.f), 448.f), fminf(fmaxf(v1[2], -448.f), 448.f), fminf(fmaxf(v1[3], -448.f), 448.f));
;                     *(v2u*)(rowp + bj * 128) = w; } }
.LBB0_2481:
	v_lshl_add_u32 v8, s46, 8, v50
	v_ashrrev_i32_e32 v9, 31, v8
	s_nop 7
	s_nop 7
	s_nop 3
	v_lshl_add_u64 v[4:5], v[8:9], 2, s[8:9]
	global_load_dword v2, v[4:5], off
	global_load_dword v22, v[4:5], off offset:64
	global_load_dword v23, v[4:5], off offset:128
	global_load_dword v24, v[4:5], off offset:192
	global_load_dword v25, v[4:5], off offset:512
	global_load_dword v26, v[4:5], off offset:576
	global_load_dword v27, v[4:5], off offset:640
	global_load_dword v28, v[4:5], off offset:704
	s_mov_b32 s13, 0xc3e00000
	v_lshl_or_b32 v6, s44, 8, v186
	v_ashrrev_i32_e32 v7, 31, v6
	s_mov_b64 s[2:3], 0x20000
	s_waitcnt vmcnt(0) lgkmcnt(0)
	v_mul_f32_e32 v10, 0x42800000, v2
	v_pk_mul_f32 v[12:13], v[162:163], v[10:11] op_sel_hi:[1,0]
	v_pk_mul_f32 v[14:15], v[160:161], v[10:11] op_sel_hi:[1,0]
	v_lshlrev_b64 v[2:3], 10, v[8:9]
	v_pk_mul_f32 v[16:17], v[158:159], v[10:11] op_sel_hi:[1,0]
	v_pk_mul_f32 v[18:19], v[156:157], v[10:11] op_sel_hi:[1,0]
	v_med3_f32 v9, v14, s13, v236
	v_med3_f32 v11, v15, s13, v236
	v_med3_f32 v14, v12, s13, v236
	v_mov_b32_e32 v12, v51
	v_cvt_pk_fp8_f32 v12, v9, v11
	v_med3_f32 v13, v13, s13, v236
	v_med3_f32 v9, v18, s13, v236
	v_med3_f32 v11, v19, s13, v236
	v_cvt_pk_fp8_f32 v12, v14, v13 op_sel:[0,0,1]
	v_mov_b32_e32 v13, v51
	v_cvt_pk_fp8_f32 v13, v9, v11
	v_med3_f32 v14, v16, s13, v236
	v_med3_f32 v15, v17, s13, v236
	v_lshl_add_u64 v[2:3], s[6:7], 0, v[2:3]
	v_cvt_pk_fp8_f32 v13, v14, v15 op_sel:[0,0,1]
	v_lshl_add_u64 v[2:3], v[2:3], 0, v[6:7]
	v_pk_mul_f32 v[14:15], v[152:153], v[10:11] op_sel_hi:[1,0]
	v_pk_mul_f32 v[16:17], v[150:151], v[10:11] op_sel_hi:[1,0]
	global_store_dwordx2 v[2:3], v[12:13], off
	v_pk_mul_f32 v[12:13], v[154:155], v[10:11] op_sel_hi:[1,0]
	v_med3_f32 v9, v14, s13, v236
	v_med3_f32 v14, v15, s13, v236
	v_med3_f32 v15, v12, s13, v236
	v_mov_b32_e32 v12, v51
	v_cvt_pk_fp8_f32 v12, v9, v14
	v_pk_mul_f32 v[10:11], v[148:149], v[10:11] op_sel_hi:[1,0]
	v_med3_f32 v13, v13, s13, v236
	v_med3_f32 v9, v10, s13, v236
	v_cvt_pk_fp8_f32 v12, v15, v13 op_sel:[0,0,1]
	v_med3_f32 v10, v11, s13, v236
	v_mov_b32_e32 v13, v51
	v_cvt_pk_fp8_f32 v13, v9, v10
	v_med3_f32 v11, v16, s13, v236
	v_med3_f32 v14, v17, s13, v236
	v_or_b32_e32 v10, 16, v8
	v_cvt_pk_fp8_f32 v13, v11, v14 op_sel:[0,0,1]
	v_ashrrev_i32_e32 v11, 31, v10
	global_store_dwordx2 v[2:3], v[12:13], off offset:128
	v_lshl_add_u64 v[12:13], v[10:11], 2, s[8:9]
	s_nop 0
	v_lshlrev_b64 v[10:11], 10, v[10:11]
	v_lshl_add_u64 v[10:11], s[6:7], 0, v[10:11]
	v_lshl_add_u64 v[10:11], v[10:11], 0, v[6:7]
	v_mov_b32_e32 v9, v22
	v_mul_f32_e32 v12, 0x42800000, v9
	v_pk_mul_f32 v[14:15], v[146:147], v[12:13] op_sel_hi:[1,0]
	v_pk_mul_f32 v[16:17], v[144:145], v[12:13] op_sel_hi:[1,0]
	v_pk_mul_f32 v[18:19], v[142:143], v[12:13] op_sel_hi:[1,0]
	v_pk_mul_f32 v[20:21], v[140:141], v[12:13] op_sel_hi:[1,0]
	v_med3_f32 v9, v16, s13, v236
	v_med3_f32 v13, v17, s13, v236
	v_med3_f32 v16, v14, s13, v236
	v_mov_b32_e32 v14, v51
	v_cvt_pk_fp8_f32 v14, v9, v13
	v_med3_f32 v15, v15, s13, v236
	v_med3_f32 v9, v20, s13, v236
	v_med3_f32 v13, v21, s13, v236
	v_cvt_pk_fp8_f32 v14, v16, v15 op_sel:[0,0,1]
	v_mov_b32_e32 v15, v51
	v_cvt_pk_fp8_f32 v15, v9, v13
	v_med3_f32 v16, v18, s13, v236
	v_med3_f32 v17, v19, s13, v236
	v_pk_mul_f32 v[18:19], v[134:135], v[12:13] op_sel_hi:[1,0]
	v_cvt_pk_fp8_f32 v15, v16, v17 op_sel:[0,0,1]
	v_pk_mul_f32 v[16:17], v[136:137], v[12:13] op_sel_hi:[1,0]
	global_store_dwordx2 v[10:11], v[14:15], off
	v_pk_mul_f32 v[14:15], v[138:139], v[12:13] op_sel_hi:[1,0]
	v_med3_f32 v9, v16, s13, v236
	v_med3_f32 v16, v17, s13, v236
	v_med3_f32 v17, v14, s13, v236
	v_mov_b32_e32 v14, v51
	v_cvt_pk_fp8_f32 v14, v9, v16
	v_pk_mul_f32 v[12:13], v[132:133], v[12:13] op_sel_hi:[1,0]
	v_med3_f32 v15, v15, s13, v236
	v_med3_f32 v9, v12, s13, v236
	v_cvt_pk_fp8_f32 v14, v17, v15 op_sel:[0,0,1]
	v_med3_f32 v12, v13, s13, v236
	v_mov_b32_e32 v15, v51
	v_cvt_pk_fp8_f32 v15, v9, v12
	v_med3_f32 v13, v18, s13, v236
	v_med3_f32 v16, v19, s13, v236
	v_cvt_pk_fp8_f32 v15, v13, v16 op_sel:[0,0,1]
	global_store_dwordx2 v[10:11], v[14:15], off offset:128
	v_or_b32_e32 v10, 32, v8
	v_ashrrev_i32_e32 v11, 31, v10
	v_lshl_add_u64 v[12:13], v[10:11], 2, s[8:9]
	s_nop 0
	v_lshlrev_b64 v[10:11], 10, v[10:11]
	v_lshl_add_u64 v[10:11], s[6:7], 0, v[10:11]
	v_lshl_add_u64 v[10:11], v[10:11], 0, v[6:7]
	v_or_b32_e32 v8, 48, v8
	v_mov_b32_e32 v9, v23
	v_mul_f32_e32 v12, 0x42800000, v9
	v_pk_mul_f32 v[14:15], v[130:131], v[12:13] op_sel_hi:[1,0]
	v_pk_mul_f32 v[16:17], v[128:129], v[12:13] op_sel_hi:[1,0]
	v_pk_mul_f32 v[18:19], v[126:127], v[12:13] op_sel_hi:[1,0]
	v_pk_mul_f32 v[20:21], v[124:125], v[12:13] op_sel_hi:[1,0]
	v_med3_f32 v9, v16, s13, v236
	v_med3_f32 v13, v17, s13, v236
	v_med3_f32 v16, v14, s13, v236
	v_mov_b32_e32 v14, v51
	v_cvt_pk_fp8_f32 v14, v9, v13
	v_med3_f32 v15, v15, s13, v236
	v_med3_f32 v9, v20, s13, v236
	v_med3_f32 v13, v21, s13, v236
	v_cvt_pk_fp8_f32 v14, v16, v15 op_sel:[0,0,1]
	v_mov_b32_e32 v15, v51
	v_cvt_pk_fp8_f32 v15, v9, v13
	v_med3_f32 v16, v18, s13, v236
	v_med3_f32 v17, v19, s13, v236
	v_pk_mul_f32 v[18:19], v[118:119], v[12:13] op_sel_hi:[1,0]
	v_cvt_pk_fp8_f32 v15, v16, v17 op_sel:[0,0,1]
	v_pk_mul_f32 v[16:17], v[120:121], v[12:13] op_sel_hi:[1,0]
	global_store_dwordx2 v[10:11], v[14:15], off
	v_pk_mul_f32 v[14:15], v[122:123], v[12:13] op_sel_hi:[1,0]
	v_med3_f32 v9, v16, s13, v236
	v_med3_f32 v16, v17, s13, v236
	v_med3_f32 v17, v14, s13, v236
	v_mov_b32_e32 v14, v51
	v_cvt_pk_fp8_f32 v14, v9, v16
	v_pk_mul_f32 v[12:13], v[116:117], v[12:13] op_sel_hi:[1,0]
	v_med3_f32 v15, v15, s13, v236
	v_med3_f32 v9, v12, s13, v236
; __device__ __forceinline__ unsigned pk4_fp8(float a, float b, float c, float d) { int w = 0; w = __builtin_amdgcn_cvt_pk_fp8_f32(a, b, w, false); w = __builtin_amdgcn_cvt_pk_fp8_f32(c, d, w, true); return (unsigned)w; }
;     __device__ __forceinline__ void operator()(EPI_SIG) const {
;         const int row0 = u.pm * 256 + wr * 64 + fr, col0 = u.pn * 256 + wc * 32 + 8 * fq;
; #pragma unroll
;         for (int ai = 0; ai < 2; ++ai)
; #pragma unroll
;             for (int m = 0; m < 4; ++m) { const int row = row0 + ai * 128 + m * 16; const float s = roww[row] * 64.0f; unsigned char* rowp = O + (size_t)row * 1024 + col0;
; #pragma unroll
;                 for (int bj = 0; bj < 2; ++bj) { const f32x4 v0 = acc[ai][bj][m][0] * s, v1 = acc[ai][bj][m][1] * s; v2u w;
;                     w.x = pk4_fp8(fminf(fmaxf(v0[0], -448.f), 448.f), fminf(fmaxf(v0[1], -448.f), 448.f), fminf(fmaxf(v0[2], -448.f), 448.f), fminf(fmaxf(v0[3], -448.f), 448.f));
;                     w.y = pk4_fp8(fminf(fmaxf(v1[0], -448.f), 448.f), fminf(fmaxf(v1[1], -448.f), 448.f), fminf(fmaxf(v1[2], -448.f), 448.f), fminf(fmaxf(v1[3], -448.f), 448.f));
;                     *(v2u*)(rowp + bj * 128) = w; } }
	v_cvt_pk_fp8_f32 v14, v17, v15 op_sel:[0,0,1]
	v_med3_f32 v12, v13, s13, v236
	v_mov_b32_e32 v15, v51
	v_cvt_pk_fp8_f32 v15, v9, v12
	v_med3_f32 v13, v18, s13, v236
	v_med3_f32 v16, v19, s13, v236
	v_ashrrev_i32_e32 v9, 31, v8
	v_cvt_pk_fp8_f32 v15, v13, v16 op_sel:[0,0,1]
	global_store_dwordx2 v[10:11], v[14:15], off offset:128
	v_lshl_add_u64 v[10:11], v[8:9], 2, s[8:9]
	s_nop 0
	v_lshlrev_b64 v[8:9], 10, v[8:9]
	v_lshl_add_u64 v[8:9], s[6:7], 0, v[8:9]
	v_lshl_add_u64 v[6:7], v[8:9], 0, v[6:7]
	v_mov_b32_e32 v10, v24
	v_mul_f32_e32 v10, 0x42800000, v10
	v_pk_mul_f32 v[8:9], v[114:115], v[10:11] op_sel_hi:[1,0]
	v_pk_mul_f32 v[12:13], v[112:113], v[10:11] op_sel_hi:[1,0]
	v_pk_mul_f32 v[14:15], v[110:111], v[10:11] op_sel_hi:[1,0]
	v_pk_mul_f32 v[16:17], v[108:109], v[10:11] op_sel_hi:[1,0]
	v_med3_f32 v11, v12, s13, v236
	v_med3_f32 v12, v13, s13, v236
	v_med3_f32 v13, v8, s13, v236
	v_mov_b32_e32 v8, v51
	v_cvt_pk_fp8_f32 v8, v11, v12
	v_med3_f32 v9, v9, s13, v236
	v_med3_f32 v11, v16, s13, v236
	v_med3_f32 v12, v17, s13, v236
	v_cvt_pk_fp8_f32 v8, v13, v9 op_sel:[0,0,1]
	v_mov_b32_e32 v9, v51
	v_cvt_pk_fp8_f32 v9, v11, v12
	v_med3_f32 v13, v14, s13, v236
	v_med3_f32 v14, v15, s13, v236
	v_cvt_pk_fp8_f32 v9, v13, v14 op_sel:[0,0,1]
	v_pk_mul_f32 v[12:13], v[104:105], v[10:11] op_sel_hi:[1,0]
	v_pk_mul_f32 v[14:15], v[102:103], v[10:11] op_sel_hi:[1,0]
	v_med3_f32 v12, v12, s13, v236
	global_store_dwordx2 v[6:7], v[8:9], off
	v_pk_mul_f32 v[8:9], v[106:107], v[10:11] op_sel_hi:[1,0]
	v_med3_f32 v13, v13, s13, v236
	v_med3_f32 v16, v8, s13, v236
	v_mov_b32_e32 v8, v51
	v_cvt_pk_fp8_f32 v8, v12, v13
	v_pk_mul_f32 v[10:11], v[100:101], v[10:11] op_sel_hi:[1,0]
	v_med3_f32 v9, v9, s13, v236
	v_med3_f32 v10, v10, s13, v236
	v_cvt_pk_fp8_f32 v8, v16, v9 op_sel:[0,0,1]
	v_med3_f32 v11, v11, s13, v236
	v_mov_b32_e32 v9, v51
	v_cvt_pk_fp8_f32 v9, v10, v11
	v_med3_f32 v12, v14, s13, v236
	v_med3_f32 v13, v15, s13, v236
	v_cvt_pk_fp8_f32 v9, v12, v13 op_sel:[0,0,1]
	global_store_dwordx2 v[6:7], v[8:9], off offset:128
	s_nop 0
	v_mov_b32_e32 v6, v25
	v_mul_f32_e32 v8, 0x42800000, v6
	v_pk_mul_f32 v[10:11], v[98:99], v[8:9] op_sel_hi:[1,0]
	v_pk_mul_f32 v[12:13], v[96:97], v[8:9] op_sel_hi:[1,0]
	v_pk_mul_f32 v[14:15], v[94:95], v[8:9] op_sel_hi:[1,0]
	v_pk_mul_f32 v[16:17], v[92:93], v[8:9] op_sel_hi:[1,0]
	v_med3_f32 v9, v12, s13, v236
	v_med3_f32 v12, v13, s13, v236
	v_med3_f32 v13, v10, s13, v236
	v_mov_b32_e32 v10, v51
	v_cvt_pk_fp8_f32 v10, v9, v12
	v_med3_f32 v11, v11, s13, v236
	v_med3_f32 v9, v16, s13, v236
	v_med3_f32 v12, v17, s13, v236
	v_cvt_pk_fp8_f32 v10, v13, v11 op_sel:[0,0,1]
	v_mov_b32_e32 v11, v51
	v_cvt_pk_fp8_f32 v11, v9, v12
	v_med3_f32 v13, v14, s13, v236
	v_med3_f32 v14, v15, s13, v236
	v_lshl_add_u64 v[6:7], v[2:3], 0, s[2:3]
	v_cvt_pk_fp8_f32 v11, v13, v14 op_sel:[0,0,1]
	s_mov_b32 s2, 0x20000
	v_add_co_u32_e32 v12, vcc, s2, v2
	v_pk_mul_f32 v[14:15], v[86:87], v[8:9] op_sel_hi:[1,0]
	s_nop 0
	v_addc_co_u32_e32 v13, vcc, 0, v3, vcc
	global_store_dwordx2 v[12:13], v[10:11], off
	v_pk_mul_f32 v[10:11], v[90:91], v[8:9] op_sel_hi:[1,0]
	v_pk_mul_f32 v[12:13], v[88:89], v[8:9] op_sel_hi:[1,0]
	v_med3_f32 v16, v10, s13, v236
	v_med3_f32 v12, v12, s13, v236
	v_med3_f32 v13, v13, s13, v236
	v_mov_b32_e32 v10, v51
	v_cvt_pk_fp8_f32 v10, v12, v13
	v_pk_mul_f32 v[8:9], v[84:85], v[8:9] op_sel_hi:[1,0]
	v_med3_f32 v11, v11, s13, v236
	v_med3_f32 v8, v8, s13, v236
	v_cvt_pk_fp8_f32 v10, v16, v11 op_sel:[0,0,1]
	v_med3_f32 v9, v9, s13, v236
	v_mov_b32_e32 v11, v51
	v_cvt_pk_fp8_f32 v11, v8, v9
	v_med3_f32 v12, v14, s13, v236
	v_med3_f32 v13, v15, s13, v236
	s_mov_b64 s[2:3], 0x24000
	v_cvt_pk_fp8_f32 v11, v12, v13 op_sel:[0,0,1]
	global_store_dwordx2 v[6:7], v[10:11], off offset:128
	s_nop 0
	v_mov_b32_e32 v6, v26
	v_mul_f32_e32 v8, 0x42800000, v6
	v_pk_mul_f32 v[10:11], v[82:83], v[8:9] op_sel_hi:[1,0]
	v_pk_mul_f32 v[12:13], v[80:81], v[8:9] op_sel_hi:[1,0]
	v_pk_mul_f32 v[14:15], v[78:79], v[8:9] op_sel_hi:[1,0]
	v_pk_mul_f32 v[16:17], v[76:77], v[8:9] op_sel_hi:[1,0]
	v_med3_f32 v9, v12, s13, v236
	v_med3_f32 v12, v13, s13, v236
	v_med3_f32 v13, v10, s13, v236
	v_mov_b32_e32 v10, v51
	v_cvt_pk_fp8_f32 v10, v9, v12
	v_med3_f32 v11, v11, s13, v236
	v_med3_f32 v9, v16, s13, v236
	v_med3_f32 v12, v17, s13, v236
	v_cvt_pk_fp8_f32 v10, v13, v11 op_sel:[0,0,1]
	v_mov_b32_e32 v11, v51
	v_cvt_pk_fp8_f32 v11, v9, v12
	v_med3_f32 v13, v14, s13, v236
	v_med3_f32 v14, v15, s13, v236
	v_lshl_add_u64 v[6:7], v[2:3], 0, s[2:3]
; __device__ __forceinline__ unsigned pk4_fp8(float a, float b, float c, float d) { int w = 0; w = __builtin_amdgcn_cvt_pk_fp8_f32(a, b, w, false); w = __builtin_amdgcn_cvt_pk_fp8_f32(c, d, w, true); return (unsigned)w; }
;     __device__ __forceinline__ void operator()(EPI_SIG) const {
;         const int row0 = u.pm * 256 + wr * 64 + fr, col0 = u.pn * 256 + wc * 32 + 8 * fq;
; #pragma unroll
;         for (int ai = 0; ai < 2; ++ai)
; #pragma unroll
;             for (int m = 0; m < 4; ++m) { const int row = row0 + ai * 128 + m * 16; const float s = roww[row] * 64.0f; unsigned char* rowp = O + (size_t)row * 1024 + col0;
; #pragma unroll
;                 for (int bj = 0; bj < 2; ++bj) { const f32x4 v0 = acc[ai][bj][m][0] * s, v1 = acc[ai][bj][m][1] * s; v2u w;
;                     w.x = pk4_fp8(fminf(fmaxf(v0[0], -448.f), 448.f), fminf(fmaxf(v0[1], -448.f), 448.f), fminf(fmaxf(v0[2], -448.f), 448.f), fminf(fmaxf(v0[3], -448.f), 448.f));
;                     w.y = pk4_fp8(fminf(fmaxf(v1[0], -448.f), 448.f), fminf(fmaxf(v1[1], -448.f), 448.f), fminf(fmaxf(v1[2], -448.f), 448.f), fminf(fmaxf(v1[3], -448.f), 448.f));
;                     *(v2u*)(rowp + bj * 128) = w; } }
	v_cvt_pk_fp8_f32 v11, v13, v14 op_sel:[0,0,1]
	s_mov_b32 s2, 0x24000
	v_add_co_u32_e32 v12, vcc, s2, v2
	v_pk_mul_f32 v[14:15], v[70:71], v[8:9] op_sel_hi:[1,0]
	s_nop 0
	v_addc_co_u32_e32 v13, vcc, 0, v3, vcc
	global_store_dwordx2 v[12:13], v[10:11], off
	v_pk_mul_f32 v[10:11], v[74:75], v[8:9] op_sel_hi:[1,0]
	v_pk_mul_f32 v[12:13], v[72:73], v[8:9] op_sel_hi:[1,0]
	v_med3_f32 v16, v10, s13, v236
	v_med3_f32 v12, v12, s13, v236
	v_med3_f32 v13, v13, s13, v236
	v_mov_b32_e32 v10, v51
	v_cvt_pk_fp8_f32 v10, v12, v13
	v_pk_mul_f32 v[8:9], v[68:69], v[8:9] op_sel_hi:[1,0]
	v_med3_f32 v11, v11, s13, v236
	v_med3_f32 v8, v8, s13, v236
	v_cvt_pk_fp8_f32 v10, v16, v11 op_sel:[0,0,1]
	v_med3_f32 v9, v9, s13, v236
	v_mov_b32_e32 v11, v51
	v_cvt_pk_fp8_f32 v11, v8, v9
	v_med3_f32 v12, v14, s13, v236
	v_med3_f32 v13, v15, s13, v236
	s_mov_b64 s[2:3], 0x28000
	v_cvt_pk_fp8_f32 v11, v12, v13 op_sel:[0,0,1]
	global_store_dwordx2 v[6:7], v[10:11], off offset:128
	s_nop 0
	v_mov_b32_e32 v6, v27
	v_mul_f32_e32 v8, 0x42800000, v6
	v_pk_mul_f32 v[10:11], v[66:67], v[8:9] op_sel_hi:[1,0]
	v_pk_mul_f32 v[12:13], v[64:65], v[8:9] op_sel_hi:[1,0]
	v_pk_mul_f32 v[14:15], v[58:59], v[8:9] op_sel_hi:[1,0]
	v_pk_mul_f32 v[16:17], v[56:57], v[8:9] op_sel_hi:[1,0]
	v_med3_f32 v9, v12, s13, v236
	v_med3_f32 v12, v13, s13, v236
	v_med3_f32 v13, v10, s13, v236
	v_mov_b32_e32 v10, v51
	v_cvt_pk_fp8_f32 v10, v9, v12
	v_med3_f32 v11, v11, s13, v236
	v_med3_f32 v9, v16, s13, v236
	v_med3_f32 v12, v17, s13, v236
	v_cvt_pk_fp8_f32 v10, v13, v11 op_sel:[0,0,1]
	v_mov_b32_e32 v11, v51
	v_cvt_pk_fp8_f32 v11, v9, v12
	v_med3_f32 v13, v14, s13, v236
	v_med3_f32 v14, v15, s13, v236
	v_lshl_add_u64 v[6:7], v[2:3], 0, s[2:3]
	v_cvt_pk_fp8_f32 v11, v13, v14 op_sel:[0,0,1]
	s_mov_b32 s2, 0x28000
	v_add_co_u32_e32 v12, vcc, s2, v2
	v_pk_mul_f32 v[14:15], v[62:63], v[8:9] op_sel_hi:[1,0]
	s_nop 0
	v_addc_co_u32_e32 v13, vcc, 0, v3, vcc
	global_store_dwordx2 v[12:13], v[10:11], off
	v_pk_mul_f32 v[10:11], v[54:55], v[8:9] op_sel_hi:[1,0]
	v_pk_mul_f32 v[12:13], v[52:53], v[8:9] op_sel_hi:[1,0]
	v_med3_f32 v16, v10, s13, v236
	v_med3_f32 v12, v12, s13, v236
	v_med3_f32 v13, v13, s13, v236
	v_mov_b32_e32 v10, v51
	v_cvt_pk_fp8_f32 v10, v12, v13
	v_pk_mul_f32 v[8:9], v[60:61], v[8:9] op_sel_hi:[1,0]
	v_med3_f32 v11, v11, s13, v236
	v_med3_f32 v8, v8, s13, v236
	v_cvt_pk_fp8_f32 v10, v16, v11 op_sel:[0,0,1]
	v_med3_f32 v9, v9, s13, v236
	v_mov_b32_e32 v11, v51
	v_cvt_pk_fp8_f32 v11, v8, v9
	v_med3_f32 v12, v14, s13, v236
	v_med3_f32 v13, v15, s13, v236
	s_mov_b64 s[2:3], 0x2c000
	v_cvt_pk_fp8_f32 v11, v12, v13 op_sel:[0,0,1]
	global_store_dwordx2 v[6:7], v[10:11], off offset:128
	s_nop 0
	v_lshl_add_u64 v[6:7], v[2:3], 0, s[2:3]
	s_mov_b32 s2, 0x2c000
	v_add_co_u32_e32 v2, vcc, s2, v2
	s_mov_b64 s[2:3], -1
	s_nop 0
	v_addc_co_u32_e32 v3, vcc, 0, v3, vcc
	s_andn2_b64 vcc, exec, s[0:1]
	v_mov_b32_e32 v4, v28
	v_mul_f32_e32 v4, 0x42800000, v4
	v_pk_mul_f32 v[8:9], v[40:41], v[4:5] op_sel_hi:[1,0]
	v_pk_mul_f32 v[10:11], v[38:39], v[4:5] op_sel_hi:[1,0]
	v_pk_mul_f32 v[12:13], v[36:37], v[4:5] op_sel_hi:[1,0]
	v_pk_mul_f32 v[14:15], v[34:35], v[4:5] op_sel_hi:[1,0]
	v_med3_f32 v5, v10, s13, v236
	v_med3_f32 v10, v11, s13, v236
	v_med3_f32 v11, v8, s13, v236
	v_mov_b32_e32 v8, v51
	v_cvt_pk_fp8_f32 v8, v5, v10
	v_med3_f32 v9, v9, s13, v236
	v_med3_f32 v5, v14, s13, v236
	v_med3_f32 v10, v15, s13, v236
	v_cvt_pk_fp8_f32 v8, v11, v9 op_sel:[0,0,1]
	v_mov_b32_e32 v9, v51
	v_cvt_pk_fp8_f32 v9, v5, v10
	v_med3_f32 v11, v12, s13, v236
	v_med3_f32 v12, v13, s13, v236
	v_cvt_pk_fp8_f32 v9, v11, v12 op_sel:[0,0,1]
	v_pk_mul_f32 v[10:11], v[48:49], v[4:5] op_sel_hi:[1,0]
	global_store_dwordx2 v[2:3], v[8:9], off
	v_pk_mul_f32 v[2:3], v[44:45], v[4:5] op_sel_hi:[1,0]
	v_pk_mul_f32 v[8:9], v[42:43], v[4:5] op_sel_hi:[1,0]
	v_med3_f32 v12, v2, s13, v236
	v_med3_f32 v8, v8, s13, v236
	v_med3_f32 v9, v9, s13, v236
	v_mov_b32_e32 v2, v51
	v_cvt_pk_fp8_f32 v2, v8, v9
	v_pk_mul_f32 v[4:5], v[46:47], v[4:5] op_sel_hi:[1,0]
	v_med3_f32 v3, v3, s13, v236
	v_med3_f32 v4, v4, s13, v236
	v_cvt_pk_fp8_f32 v2, v12, v3 op_sel:[0,0,1]
	v_med3_f32 v5, v5, s13, v236
	v_mov_b32_e32 v3, v51
	v_cvt_pk_fp8_f32 v3, v4, v5
	v_med3_f32 v8, v10, s13, v236
	v_med3_f32 v9, v11, s13, v236
	v_cvt_pk_fp8_f32 v3, v8, v9 op_sel:[0,0,1]
	global_store_dwordx2 v[6:7], v[2:3], off offset:128
	s_cbranch_vccnz .LBB0_2474
	s_andn2_b64 vcc, exec, s[4:5]
	s_cbranch_vccnz .LBB0_2473
	s_barrier
	s_branch .LBB0_2473
